# v64 plus s_setprio 1 over the dependent q*S / state-update / o-write chain of each recurrence chunk
# baseline (speedup 1.0000x reference)
; #define LAS __attribute__((address_space(3)))
; __device__ __forceinline__ unsigned pk2(float lo, float hi) { return pg8::cvt_pk_bf16(lo, hi); }
; __device__ __forceinline__ void hg_recur(LAS unsigned char* lds, const bf16_t* QF, bf16_t* IG, const bf16_t* P, const float* Dg, float* ssq_o, int G, int bid) {
;     ...
;             f32x4 o0 = (f32x4){0.f, 0.f, 0.f, 0.f}, o1 = o0;
; #pragma unroll
;             for (int k2 = 0; k2 < 2; ++k2) {
;                 u32x2 sbu; sbu.x = pk2(S[k2][0], S[k2][1]); sbu.y = pk2(S[k2][2], S[k2][3]);
;                 const s16x4 Sb = __builtin_bit_cast(s16x4, sbu);
;                 const LAS unsigned char* qp = sb + H3_Q + lv * H3_QP + (32 * kq + 16 * k2 + 4 * fq) * 2;
;                 const s16x4 a0 = *(const LAS s16x4*)qp, a1 = *(const LAS s16x4*)(qp + 16 * H3_QP);
;                 o0 = __builtin_amdgcn_mfma_f32_16x16x16bf16_1k(a0, Sb, o0, 0, 0, 0);
;                 o1 = __builtin_amdgcn_mfma_f32_16x16x16bf16_1k(a1, Sb, o1, 0, 0, 0);
;             }
;             if (kq < 3) {
;                 const LAS unsigned char* pp = sb + H3_P + (16 * (kq > 0 ? 1 : 0) + lv) * H3_PP + (16 * (kq == 2 ? 1 : 0) + 4 * fq) * 2;
;                 const s16x4 a = *(const LAS s16x4*)pp;
;                 if (kq == 0) o0 = __builtin_amdgcn_mfma_f32_16x16x16bf16_1k(a, vf0, o0, 0, 0, 0);
;                 else if (kq == 1) o1 = __builtin_amdgcn_mfma_f32_16x16x16bf16_1k(a, vf0, o1, 0, 0, 0);
;                 else o1 = __builtin_amdgcn_mfma_f32_16x16x16bf16_1k(a, vf1, o1, 0, 0, 0);
;             }
.LBB0_506:
	s_or_b64 exec, exec, s[58:59]
	s_setprio 1
	v_cvt_pk_bf16_f32 v112, v28, v29
	v_cvt_pk_bf16_f32 v113, v30, v31
	s_nop 0
	s_nop 0
	v_cvt_pk_bf16_f32 v116, v24, v25
	v_cvt_pk_bf16_f32 v117, v26, v27
	s_nop 0
	s_nop 0
	s_waitcnt lgkmcnt(8)
	v_mfma_f32_16x16x16_bf16 v[80:83], v[130:131], v[112:113], 0
	v_lshlrev_b32_e32 v39, 16, v39
	v_or_b32_sdwa v78, v39, v33 dst_sel:DWORD dst_unused:UNUSED_PAD src0_sel:DWORD src1_sel:WORD_0
	v_lshlrev_b32_e32 v33, 16, v34
	s_waitcnt lgkmcnt(7)
	v_mfma_f32_16x16x16_bf16 v[112:115], v[132:133], v[112:113], 0
	v_lshlrev_b32_e32 v39, 16, v35
	v_or_b32_sdwa v79, v33, v32 dst_sel:DWORD dst_unused:UNUSED_PAD src0_sel:DWORD src1_sel:WORD_0
	s_waitcnt lgkmcnt(6)
	v_mfma_f32_16x16x16_bf16 v[32:35], v[134:135], v[116:117], v[80:83]
	s_nop 2
	v_or_b32_sdwa v80, v39, v36 dst_sel:DWORD dst_unused:UNUSED_PAD src0_sel:DWORD src1_sel:WORD_0
	v_lshlrev_b32_e32 v36, 16, v38
	v_or_b32_sdwa v81, v36, v37 dst_sel:DWORD dst_unused:UNUSED_PAD src0_sel:DWORD src1_sel:WORD_0
	s_waitcnt lgkmcnt(5)
	v_mfma_f32_16x16x16_bf16 v[36:39], v[136:137], v[116:117], v[112:115]
	s_and_saveexec_b64 s[58:59], s[16:17]
	s_cbranch_execz .LBB0_516
	s_nop 0
	s_and_saveexec_b64 s[36:37], s[42:43]
	s_xor_b64 s[60:61], exec, s[36:37]
	s_cbranch_execz .LBB0_513
	s_and_saveexec_b64 s[36:37], s[18:19]
	s_xor_b64 s[62:63], exec, s[36:37]
	s_cbranch_execz .LBB0_510
	s_waitcnt lgkmcnt(4)
	v_mfma_f32_16x16x16_bf16 v[36:39], v[138:139], v[80:81], v[36:39]

; #define LAS __attribute__((address_space(3)))
; #define LDS_BARRIER() do { asm volatile("s_waitcnt lgkmcnt(0)" ::: "memory"); __builtin_amdgcn_s_barrier(); asm volatile("" ::: "memory"); } while (0)
; __device__ __forceinline__ void hg_recur(LAS unsigned char* lds, const bf16_t* QF, bf16_t* IG, const bf16_t* P, const float* Dg, float* ssq_o, int G, int bid) {
;     ...
; #pragma unroll
;             for (int k2 = 0; k2 < 2; ++k2) {
;                 const f32x4 dd = *(const LAS f32x4*)(sb + H3_D + (32 * kq + 16 * k2 + 4 * fq) * 4);
;                 S[k2] = S[k2] * dd;
;                 const LAS unsigned char* kp = sb + H3_K + (32 * kq + 16 * k2 + lv) * H3_KP + 4 * fq * 2;
;                 const s16x4 a0 = *(const LAS s16x4*)kp, a1 = *(const LAS s16x4*)(kp + 32);
;                 S[k2] = __builtin_amdgcn_mfma_f32_16x16x16bf16_1k(a0, vf0, S[k2], 0, 0, 0);
;                 S[k2] = __builtin_amdgcn_mfma_f32_16x16x16bf16_1k(a1, vf1, S[k2], 0, 0, 0);
;             }
;             { LAS float* ot = (LAS float*)(lds + H3_O + st * H3_OBYTES) + kq * 1024 + 16 * vt + lv;
; #pragma unroll
;               for (int i = 0; i < 4; ++i) { ot[(4 * fq + i) * 32] = o0[i]; ot[(16 + 4 * fq + i) * 32] = o1[i]; } }
;             LDS_BARRIER();
.LBB0_516:
	s_or_b64 exec, exec, s[58:59]
	s_nop 0
	s_nop 0
	s_nop 0
	s_add_i32 s36, s35, 1
	s_cmpk_gt_u32 s36, 0xfe
	s_waitcnt lgkmcnt(2)
	v_pk_mul_f32 v[30:31], v[30:31], v[146:147]
	v_pk_mul_f32 v[28:29], v[28:29], v[144:145]
	s_nop 0
	s_waitcnt lgkmcnt(1)
	v_pk_mul_f32 v[26:27], v[26:27], v[150:151]
	v_pk_mul_f32 v[24:25], v[24:25], v[148:149]
	v_mfma_f32_16x16x16_bf16 v[28:31], v[140:141], v[78:79], v[28:31]
	ds_write2_b32 v92, v32, v33 offset1:32
	ds_write2_b32 v108, v36, v37 offset1:32
	ds_write2_b32 v92, v34, v35 offset0:64 offset1:96
	ds_write2_b32 v108, v38, v39 offset0:64 offset1:96
	s_waitcnt lgkmcnt(0)
	s_waitcnt lgkmcnt(4)
	v_mfma_f32_16x16x16_bf16 v[24:27], v[152:153], v[78:79], v[24:27]
	s_setprio 0
	s_barrier
	v_mfma_f32_16x16x16_bf16 v[28:31], v[142:143], v[80:81], v[28:31]
	v_mfma_f32_16x16x16_bf16 v[24:27], v[154:155], v[80:81], v[24:27]
	s_cbranch_scc1 .LBB0_528
	s_waitcnt vmcnt(2)
	ds_write_b128 v105, v[8:11]
	s_waitcnt vmcnt(1)
	ds_write_b128 v97, v[12:15] offset:8704
	s_and_saveexec_b64 s[36:37], s[8:9]
	s_xor_b64 s[58:59], exec, s[36:37]
	s_cbranch_execz .LBB0_525
	s_and_saveexec_b64 s[36:37], s[10:11]
	s_xor_b64 s[60:61], exec, s[36:37]
	s_cbranch_execz .LBB0_522
	s_and_saveexec_b64 s[62:63], s[12:13]
	v_add_u32_e32 v32, 0, v86
	ds_write_b128 v32, v[0:3] offset:19968
	s_or_b64 exec, exec, s[62:63]

; #define LAS __attribute__((address_space(3)))
; __device__ __forceinline__ unsigned pk2(float lo, float hi) { return pg8::cvt_pk_bf16(lo, hi); }
; __device__ __forceinline__ void hg_recur(LAS unsigned char* lds, const bf16_t* QF, bf16_t* IG, const bf16_t* P, const float* Dg, float* ssq_o, int G, int bid) {
;     ...
;             f32x4 o0 = (f32x4){0.f, 0.f, 0.f, 0.f}, o1 = o0;
; #pragma unroll
;             for (int k2 = 0; k2 < 2; ++k2) {
;                 u32x2 sbu; sbu.x = pk2(S[k2][0], S[k2][1]); sbu.y = pk2(S[k2][2], S[k2][3]);
;                 const s16x4 Sb = __builtin_bit_cast(s16x4, sbu);
;                 const LAS unsigned char* qp = sb + H3_Q + lv * H3_QP + (32 * kq + 16 * k2 + 4 * fq) * 2;
;                 const s16x4 a0 = *(const LAS s16x4*)qp, a1 = *(const LAS s16x4*)(qp + 16 * H3_QP);
;                 o0 = __builtin_amdgcn_mfma_f32_16x16x16bf16_1k(a0, Sb, o0, 0, 0, 0);
;                 o1 = __builtin_amdgcn_mfma_f32_16x16x16bf16_1k(a1, Sb, o1, 0, 0, 0);
;             }
;             if (kq < 3) {
;                 const LAS unsigned char* pp = sb + H3_P + (16 * (kq > 0 ? 1 : 0) + lv) * H3_PP + (16 * (kq == 2 ? 1 : 0) + 4 * fq) * 2;
;                 const s16x4 a = *(const LAS s16x4*)pp;
;                 if (kq == 0) o0 = __builtin_amdgcn_mfma_f32_16x16x16bf16_1k(a, vf0, o0, 0, 0, 0);
;                 else if (kq == 1) o1 = __builtin_amdgcn_mfma_f32_16x16x16bf16_1k(a, vf0, o1, 0, 0, 0);
;                 else o1 = __builtin_amdgcn_mfma_f32_16x16x16bf16_1k(a, vf1, o1, 0, 0, 0);
;             }
.LBB0_540:
	s_or_b64 exec, exec, s[56:57]
	s_setprio 1
	v_cvt_pk_bf16_f32 v112, v28, v29
	v_cvt_pk_bf16_f32 v113, v30, v31
	s_nop 0
	s_nop 0
	v_cvt_pk_bf16_f32 v116, v24, v25
	v_cvt_pk_bf16_f32 v117, v26, v27
	s_nop 0
	s_nop 0
	s_waitcnt lgkmcnt(8)
	v_mfma_f32_16x16x16_bf16 v[80:83], v[130:131], v[112:113], 0
	v_lshlrev_b32_e32 v39, 16, v39
	v_or_b32_sdwa v78, v39, v33 dst_sel:DWORD dst_unused:UNUSED_PAD src0_sel:DWORD src1_sel:WORD_0
	v_lshlrev_b32_e32 v33, 16, v34
	s_waitcnt lgkmcnt(7)
	v_mfma_f32_16x16x16_bf16 v[112:115], v[132:133], v[112:113], 0
	v_lshlrev_b32_e32 v39, 16, v35
	v_or_b32_sdwa v79, v33, v32 dst_sel:DWORD dst_unused:UNUSED_PAD src0_sel:DWORD src1_sel:WORD_0
	s_waitcnt lgkmcnt(6)
	v_mfma_f32_16x16x16_bf16 v[32:35], v[134:135], v[116:117], v[80:83]
	s_nop 2
	v_or_b32_sdwa v80, v39, v36 dst_sel:DWORD dst_unused:UNUSED_PAD src0_sel:DWORD src1_sel:WORD_0
	v_lshlrev_b32_e32 v36, 16, v38
	v_or_b32_sdwa v81, v36, v37 dst_sel:DWORD dst_unused:UNUSED_PAD src0_sel:DWORD src1_sel:WORD_0
	s_waitcnt lgkmcnt(5)
	v_mfma_f32_16x16x16_bf16 v[36:39], v[136:137], v[116:117], v[112:115]
	s_and_saveexec_b64 s[56:57], s[16:17]
	s_cbranch_execz .LBB0_550
	s_nop 0
	s_and_saveexec_b64 s[36:37], s[42:43]
	s_xor_b64 s[58:59], exec, s[36:37]
	s_cbranch_execz .LBB0_547
	s_and_saveexec_b64 s[36:37], s[18:19]
	s_xor_b64 s[60:61], exec, s[36:37]
	s_cbranch_execz .LBB0_544
	s_waitcnt lgkmcnt(4)
	v_mfma_f32_16x16x16_bf16 v[36:39], v[138:139], v[80:81], v[36:39]

; #define LAS __attribute__((address_space(3)))
; #define LDS_BARRIER() do { asm volatile("s_waitcnt lgkmcnt(0)" ::: "memory"); __builtin_amdgcn_s_barrier(); asm volatile("" ::: "memory"); } while (0)
; __device__ __forceinline__ void hg_recur(LAS unsigned char* lds, const bf16_t* QF, bf16_t* IG, const bf16_t* P, const float* Dg, float* ssq_o, int G, int bid) {
;     ...
; #pragma unroll
;             for (int k2 = 0; k2 < 2; ++k2) {
;                 const f32x4 dd = *(const LAS f32x4*)(sb + H3_D + (32 * kq + 16 * k2 + 4 * fq) * 4);
;                 S[k2] = S[k2] * dd;
;                 const LAS unsigned char* kp = sb + H3_K + (32 * kq + 16 * k2 + lv) * H3_KP + 4 * fq * 2;
;                 const s16x4 a0 = *(const LAS s16x4*)kp, a1 = *(const LAS s16x4*)(kp + 32);
;                 S[k2] = __builtin_amdgcn_mfma_f32_16x16x16bf16_1k(a0, vf0, S[k2], 0, 0, 0);
;                 S[k2] = __builtin_amdgcn_mfma_f32_16x16x16bf16_1k(a1, vf1, S[k2], 0, 0, 0);
;             }
;             { LAS float* ot = (LAS float*)(lds + H3_O + st * H3_OBYTES) + kq * 1024 + 16 * vt + lv;
; #pragma unroll
;               for (int i = 0; i < 4; ++i) { ot[(4 * fq + i) * 32] = o0[i]; ot[(16 + 4 * fq + i) * 32] = o1[i]; } }
;             LDS_BARRIER();
.LBB0_550:
	s_or_b64 exec, exec, s[56:57]
	s_nop 0
	s_nop 0
	s_nop 0
	v_add_u32_e32 v72, 64, v72
	v_lshl_add_u64 v[74:75], v[74:75], 0, s[46:47]
	v_lshl_add_u64 v[76:77], v[76:77], 0, s[48:49]
	s_waitcnt lgkmcnt(2)
	v_pk_mul_f32 v[30:31], v[30:31], v[146:147]
	v_pk_mul_f32 v[28:29], v[28:29], v[144:145]
	s_nop 0
	s_waitcnt lgkmcnt(1)
	v_pk_mul_f32 v[26:27], v[26:27], v[150:151]
	v_pk_mul_f32 v[24:25], v[24:25], v[148:149]
	v_mfma_f32_16x16x16_bf16 v[28:31], v[140:141], v[78:79], v[28:31]
	ds_write2_b32 v110, v32, v33 offset1:32
	ds_write2_b32 v111, v36, v37 offset1:32
	ds_write2_b32 v110, v34, v35 offset0:64 offset1:96
	ds_write2_b32 v111, v38, v39 offset0:64 offset1:96
	s_waitcnt lgkmcnt(0)
	s_waitcnt lgkmcnt(4)
	v_mfma_f32_16x16x16_bf16 v[24:27], v[152:153], v[78:79], v[24:27]
	s_setprio 0
	s_barrier
	s_and_b64 vcc, exec, s[54:55]
	v_mfma_f32_16x16x16_bf16 v[28:31], v[142:143], v[80:81], v[28:31]
	v_mfma_f32_16x16x16_bf16 v[24:27], v[154:155], v[80:81], v[24:27]
	s_cbranch_vccnz .LBB0_552
	s_mov_b32 s35, s33
	s_branch .LBB0_484
